# phase 12 (two small-K GEMMs hipcc had fully unrolled): tile bodies replaced by the LDS-DMA K-loop + dwordx2-store bf16 epilogue
# speedup vs baseline: 1.0139x; 1.0020x over previous
; #define G_LOAD(KT) do { _Pragma("unroll") for (int i = 0; i < 4; ++i) { ra[i] = *(const u32x4*)(Ag + (size_t)i * 64 * lda + (KT) * 64); rb[i] = *(const u32x4*)(Bg + (size_t)i * 64 * K + (KT) * 64); } } while (0)
; #define G_STORE(BUF) do { u16* ad = As + (BUF) * 256 * 64 + sto; u16* bd = Bs + (BUF) * 256 * 64 + sto; _Pragma("unroll") for (int i = 0; i < 4; ++i) { *(u32x4*)(ad + i * 64 * 64) = ra[i]; *(u32x4*)(bd + i * 64 * 64) = rb[i]; } } while (0)
; template <int EPI>
; DI void gemm_phase(const u16* __restrict__ A, int lda, const u16* __restrict__ Bt, int K, int N, u16* outb, int ldo,
;                    const float* r0, const float* r1, float* outf, char* lds, int bid, int nb) {
;     ...
;     if (swz) { const int st = xcd + 8 * it, sm = st / nSN, sn = st - sm * nSN; tm = sm * GM + jb / GN; tn = sn * GN + (jb % GN); }
;     else { const int t = bid + it * nb; tm = t / nN; tn = t - tm * nN; }
;     const u16* Ag = A + (size_t)(tm * 256 + lrow) * lda + lch * 8;
;     const u16* Bg = Bt + (size_t)(tn * 256 + lrow) * K + lch * 8;
;     f32x4 acc[8][4];
; #pragma unroll
;     for (int i = 0; i < 8; ++i)
; #pragma unroll
;       for (int j = 0; j < 4; ++j) acc[i][j] = (f32x4){0.f, 0.f, 0.f, 0.f};
;     u32x4 ra[4], rb[4];
;     ...
;     G_LOAD(0);
;     G_STORE(0);
;     __syncthreads();
;     for (int kt = 0; kt < nk; ++kt) {
;       const int cur = kt & 1;
;       if (kt + 1 < nk) G_LOAD(kt + 1);
;       G_MMA(cur, fo0);
;       G_MMA(cur, fo1);
.LBB0_999:
	s_lshl_b32 s29, s38, 8
	s_lshl_b32 s96, s37, 8
	v_readfirstlane_b32 vcc_hi, v174
	s_lshr_b32 vcc_hi, vcc_hi, 6
	s_lshl_b32 vcc_hi, vcc_hi, 3
	s_add_u32 vcc_lo, vcc_hi, s29
	s_mul_i32 vcc_lo, vcc_lo, 0x300
	s_add_u32 s98, s24, vcc_lo
	s_addc_u32 s99, s25, 0
	s_add_u32 s98, s98, 0x3600000
	s_addc_u32 s99, s99, 0
	s_add_u32 vcc_lo, vcc_hi, s96
	s_mul_i32 vcc_lo, vcc_lo, 0x300
	s_add_u32 s100, s24, vcc_lo
	s_addc_u32 s101, s25, 0
	s_add_u32 s100, s100, 0x1900000
	s_addc_u32 s101, s101, 0
	v_and_b32_e32 v229, 63, v174
	v_lshrrev_b32_e32 v230, 3, v229
	v_mov_b32_e32 v233, 0x300
	v_mul_u32_u24_e32 v224, v230, v233
	v_bfe_u32 v231, v174, 4, 2
	v_bfe_u32 v232, v174, 6, 1
	v_lshl_or_b32 v232, v232, 2, v231
	v_and_b32_e32 v233, 7, v174
	v_xor_b32_e32 v232, v232, v233
	v_lshl_add_u32 v224, v232, 4, v224
	v_and_b32_e32 v229, 15, v174
	v_bfe_u32 v230, v174, 1, 3
	v_xor_b32_e32 v230, v230, v231
	v_lshlrev_b32_e32 v230, 4, v230
	v_lshl_or_b32 v230, v229, 7, v230
	v_lshrrev_b32_e32 v229, 8, v174
	v_lshl_or_b32 v225, v229, 14, v230
	v_bfe_u32 v229, v174, 6, 2
	v_lshl_or_b32 v227, v229, 13, v230
	v_or_b32_e32 v227, 0x10000, v227
	v_xor_b32_e32 v226, 64, v225
	v_xor_b32_e32 v228, 64, v227
	v_readfirstlane_b32 s97, v174
	s_lshl_b32 s97, s97, 4
	s_mov_b32 s28, 4
	s_add_u32 m0, s97, 0x0
	s_add_u32 s10, s98, 0x0
	s_addc_u32 s11, s99, 0
	global_load_lds_dwordx4 v224, s[10:11]
	s_add_u32 m0, s97, 0x10000
	s_add_u32 s10, s100, 0x0
	s_addc_u32 s11, s101, 0
	global_load_lds_dwordx4 v224, s[10:11]
	s_add_u32 m0, s97, 0x2000
	s_add_u32 s10, s98, 0xc000
	s_addc_u32 s11, s99, 0
	global_load_lds_dwordx4 v224, s[10:11]
	s_add_u32 m0, s97, 0x12000
	s_add_u32 s10, s100, 0xc000
	s_addc_u32 s11, s101, 0
	global_load_lds_dwordx4 v224, s[10:11]
	s_add_u32 m0, s97, 0x4000
	s_add_u32 s10, s98, 0x18000
	s_addc_u32 s11, s99, 0
	global_load_lds_dwordx4 v224, s[10:11]
	s_add_u32 m0, s97, 0x14000
	s_add_u32 s10, s100, 0x18000
	s_addc_u32 s11, s101, 0
	global_load_lds_dwordx4 v224, s[10:11]
	s_add_u32 m0, s97, 0x6000
	s_add_u32 s10, s98, 0x24000
	s_addc_u32 s11, s99, 0
	global_load_lds_dwordx4 v224, s[10:11]
	s_add_u32 m0, s97, 0x16000
	s_add_u32 s10, s100, 0x24000
	s_addc_u32 s11, s101, 0
	global_load_lds_dwordx4 v224, s[10:11]
	s_add_u32 m0, s97, 0x8000
	s_add_u32 s10, s98, 0x80
	s_addc_u32 s11, s99, 0
	global_load_lds_dwordx4 v224, s[10:11]
	s_add_u32 m0, s97, 0x18000
	s_add_u32 s10, s100, 0x80
	s_addc_u32 s11, s101, 0
	global_load_lds_dwordx4 v224, s[10:11]
	s_add_u32 m0, s97, 0xa000
	s_add_u32 s10, s98, 0xc080
	s_addc_u32 s11, s99, 0
	global_load_lds_dwordx4 v224, s[10:11]
	s_add_u32 m0, s97, 0x1a000
	s_add_u32 s10, s100, 0xc080
	s_addc_u32 s11, s101, 0
	global_load_lds_dwordx4 v224, s[10:11]
	s_add_u32 m0, s97, 0xc000
	s_add_u32 s10, s98, 0x18080
	s_addc_u32 s11, s99, 0
	global_load_lds_dwordx4 v224, s[10:11]
	s_add_u32 m0, s97, 0x1c000
	s_add_u32 s10, s100, 0x18080
	s_addc_u32 s11, s101, 0
	global_load_lds_dwordx4 v224, s[10:11]
	s_add_u32 m0, s97, 0xe000
	s_add_u32 s10, s98, 0x24080
	s_addc_u32 s11, s99, 0
	global_load_lds_dwordx4 v224, s[10:11]
	s_add_u32 m0, s97, 0x1e000
	s_add_u32 s10, s100, 0x24080
	s_addc_u32 s11, s101, 0
	global_load_lds_dwordx4 v224, s[10:11]
	s_add_u32 s98, s98, 0x100
	s_addc_u32 s99, s99, 0
	s_add_u32 s100, s100, 0x100
	s_addc_u32 s101, s101, 0
	s_waitcnt vmcnt(8)
	s_barrier
	ds_read_b128 v[152:155], v227 offset:0
	ds_read_b128 v[156:159], v227 offset:2048
	ds_read_b128 v[160:163], v227 offset:4096
	ds_read_b128 v[164:167], v227 offset:6144
	ds_read_b128 v[188:191], v225 offset:0
	ds_read_b128 v[192:195], v225 offset:2048
	ds_read_b128 v[196:199], v225 offset:4096
	ds_read_b128 v[200:203], v225 offset:6144
	ds_read_b128 v[204:207], v225 offset:8192
	ds_read_b128 v[208:211], v225 offset:10240
	ds_read_b128 v[212:215], v225 offset:12288
	ds_read_b128 v[216:219], v225 offset:14336
	v_xor_b32_e32 v225, 0x8000, v225
	v_xor_b32_e32 v227, 0x8000, v227
	s_waitcnt lgkmcnt(0)
	s_waitcnt lgkmcnt(4)
	v_mfma_f32_16x16x32_bf16 v[124:127], v[152:155], v[188:191], 0
	v_mfma_f32_16x16x32_bf16 v[120:123], v[156:159], v[188:191], 0
	v_mfma_f32_16x16x32_bf16 v[116:119], v[160:163], v[188:191], 0
	v_mfma_f32_16x16x32_bf16 v[112:115], v[164:167], v[188:191], 0
	ds_read_b128 v[188:191], v226 offset:0
	ds_read_b128 v[168:171], v228 offset:0
	v_mfma_f32_16x16x32_bf16 v[108:111], v[152:155], v[192:195], 0
	v_mfma_f32_16x16x32_bf16 v[104:107], v[156:159], v[192:195], 0
	v_mfma_f32_16x16x32_bf16 v[100:103], v[160:163], v[192:195], 0
	v_mfma_f32_16x16x32_bf16 v[96:99], v[164:167], v[192:195], 0
	ds_read_b128 v[192:195], v226 offset:2048
	ds_read_b128 v[176:179], v228 offset:2048
	v_mfma_f32_16x16x32_bf16 v[92:95], v[152:155], v[196:199], 0
	v_mfma_f32_16x16x32_bf16 v[88:91], v[156:159], v[196:199], 0
	v_mfma_f32_16x16x32_bf16 v[84:87], v[160:163], v[196:199], 0
	v_mfma_f32_16x16x32_bf16 v[80:83], v[164:167], v[196:199], 0
	ds_read_b128 v[196:199], v226 offset:4096
	ds_read_b128 v[180:183], v228 offset:4096
	v_mfma_f32_16x16x32_bf16 v[76:79], v[152:155], v[200:203], 0
	v_mfma_f32_16x16x32_bf16 v[72:75], v[156:159], v[200:203], 0
	v_mfma_f32_16x16x32_bf16 v[68:71], v[160:163], v[200:203], 0
	v_mfma_f32_16x16x32_bf16 v[64:67], v[164:167], v[200:203], 0
	ds_read_b128 v[200:203], v226 offset:6144
	ds_read_b128 v[184:187], v228 offset:6144
	s_waitcnt lgkmcnt(11)
	v_mfma_f32_16x16x32_bf16 v[60:63], v[152:155], v[204:207], 0
	v_mfma_f32_16x16x32_bf16 v[56:59], v[156:159], v[204:207], 0
	v_mfma_f32_16x16x32_bf16 v[52:55], v[160:163], v[204:207], 0
	v_mfma_f32_16x16x32_bf16 v[48:51], v[164:167], v[204:207], 0
	ds_read_b128 v[204:207], v226 offset:8192
	ds_read_b128 v[220:223], v226 offset:14336
	s_waitcnt lgkmcnt(11)
	v_mfma_f32_16x16x32_bf16 v[44:47], v[152:155], v[208:211], 0
	v_mfma_f32_16x16x32_bf16 v[40:43], v[156:159], v[208:211], 0
	v_mfma_f32_16x16x32_bf16 v[36:39], v[160:163], v[208:211], 0
	v_mfma_f32_16x16x32_bf16 v[32:35], v[164:167], v[208:211], 0
	ds_read_b128 v[208:211], v226 offset:10240
	s_waitcnt lgkmcnt(11)
	v_mfma_f32_16x16x32_bf16 v[28:31], v[152:155], v[212:215], 0
	v_mfma_f32_16x16x32_bf16 v[24:27], v[156:159], v[212:215], 0
	v_mfma_f32_16x16x32_bf16 v[20:23], v[160:163], v[212:215], 0
	v_mfma_f32_16x16x32_bf16 v[16:19], v[164:167], v[212:215], 0
	ds_read_b128 v[212:215], v226 offset:12288
	v_mfma_f32_16x16x32_bf16 v[12:15], v[152:155], v[216:219], 0
	v_mfma_f32_16x16x32_bf16 v[8:11], v[156:159], v[216:219], 0
	v_mfma_f32_16x16x32_bf16 v[4:7], v[160:163], v[216:219], 0
	v_mfma_f32_16x16x32_bf16 v[0:3], v[164:167], v[216:219], 0
	s_branch .Lgm8_mid0

; #define G_LOAD(KT) do { _Pragma("unroll") for (int i = 0; i < 4; ++i) { ra[i] = *(const u32x4*)(Ag + (size_t)i * 64 * lda + (KT) * 64); rb[i] = *(const u32x4*)(Bg + (size_t)i * 64 * K + (KT) * 64); } } while (0)
; #define G_STORE(BUF) do { u16* ad = As + (BUF) * 256 * 64 + sto; u16* bd = Bs + (BUF) * 256 * 64 + sto; _Pragma("unroll") for (int i = 0; i < 4; ++i) { *(u32x4*)(ad + i * 64 * 64) = ra[i]; *(u32x4*)(bd + i * 64 * 64) = rb[i]; } } while (0)
; template <int EPI>
; DI void gemm_phase(const u16* __restrict__ A, int lda, const u16* __restrict__ Bt, int K, int N, u16* outb, int ldo,
;                    const float* r0, const float* r1, float* outf, char* lds, int bid, int nb) {
;     ...
;     for (int kt = 0; kt < nk; ++kt) {
;       const int cur = kt & 1;
;       if (kt + 1 < nk) G_LOAD(kt + 1);
;       G_MMA(cur, fo0);
;       G_MMA(cur, fo1);
;       if (kt + 1 < nk) G_STORE(cur ^ 1);
;       __syncthreads();
;     }
.Lgm8_mid0:
	s_waitcnt vmcnt(0) lgkmcnt(0)
	s_barrier
	v_mfma_f32_16x16x32_bf16 v[124:127], v[168:171], v[188:191], v[124:127]
	v_mfma_f32_16x16x32_bf16 v[120:123], v[176:179], v[188:191], v[120:123]
	v_mfma_f32_16x16x32_bf16 v[116:119], v[180:183], v[188:191], v[116:119]
	v_mfma_f32_16x16x32_bf16 v[112:115], v[184:187], v[188:191], v[112:115]
	ds_read_b128 v[188:191], v225 offset:0
	ds_read_b128 v[152:155], v227 offset:0
	s_add_u32 m0, s97, 0x0
	s_add_u32 s10, s98, 0x0
	s_addc_u32 s11, s99, 0
	global_load_lds_dwordx4 v224, s[10:11]
	v_mfma_f32_16x16x32_bf16 v[108:111], v[168:171], v[192:195], v[108:111]
	v_mfma_f32_16x16x32_bf16 v[104:107], v[176:179], v[192:195], v[104:107]
	v_mfma_f32_16x16x32_bf16 v[100:103], v[180:183], v[192:195], v[100:103]
	v_mfma_f32_16x16x32_bf16 v[96:99], v[184:187], v[192:195], v[96:99]
	ds_read_b128 v[192:195], v225 offset:2048
	ds_read_b128 v[156:159], v227 offset:2048
	s_add_u32 m0, s97, 0x10000
	s_add_u32 s10, s100, 0x0
	s_addc_u32 s11, s101, 0
	global_load_lds_dwordx4 v224, s[10:11]
	v_mfma_f32_16x16x32_bf16 v[92:95], v[168:171], v[196:199], v[92:95]
	v_mfma_f32_16x16x32_bf16 v[88:91], v[176:179], v[196:199], v[88:91]
	v_mfma_f32_16x16x32_bf16 v[84:87], v[180:183], v[196:199], v[84:87]
	v_mfma_f32_16x16x32_bf16 v[80:83], v[184:187], v[196:199], v[80:83]
	ds_read_b128 v[196:199], v225 offset:4096
	ds_read_b128 v[160:163], v227 offset:4096
	s_add_u32 m0, s97, 0x2000
	s_add_u32 s10, s98, 0xc000
	s_addc_u32 s11, s99, 0
	global_load_lds_dwordx4 v224, s[10:11]
	v_mfma_f32_16x16x32_bf16 v[76:79], v[168:171], v[200:203], v[76:79]
	v_mfma_f32_16x16x32_bf16 v[72:75], v[176:179], v[200:203], v[72:75]
	v_mfma_f32_16x16x32_bf16 v[68:71], v[180:183], v[200:203], v[68:71]
	v_mfma_f32_16x16x32_bf16 v[64:67], v[184:187], v[200:203], v[64:67]
	ds_read_b128 v[200:203], v225 offset:6144
	ds_read_b128 v[164:167], v227 offset:6144
	s_add_u32 m0, s97, 0x12000
	s_add_u32 s10, s100, 0xc000
	s_addc_u32 s11, s101, 0
	global_load_lds_dwordx4 v224, s[10:11]
	v_mfma_f32_16x16x32_bf16 v[60:63], v[168:171], v[204:207], v[60:63]
	v_mfma_f32_16x16x32_bf16 v[56:59], v[176:179], v[204:207], v[56:59]
	v_mfma_f32_16x16x32_bf16 v[52:55], v[180:183], v[204:207], v[52:55]
	v_mfma_f32_16x16x32_bf16 v[48:51], v[184:187], v[204:207], v[48:51]
	ds_read_b128 v[204:207], v225 offset:8192
	ds_read_b128 v[216:219], v225 offset:14336
	s_add_u32 m0, s97, 0x4000
	s_add_u32 s10, s98, 0x18000
	s_addc_u32 s11, s99, 0
	global_load_lds_dwordx4 v224, s[10:11]
	v_mfma_f32_16x16x32_bf16 v[44:47], v[168:171], v[208:211], v[44:47]
	v_mfma_f32_16x16x32_bf16 v[40:43], v[176:179], v[208:211], v[40:43]
	v_mfma_f32_16x16x32_bf16 v[36:39], v[180:183], v[208:211], v[36:39]
	v_mfma_f32_16x16x32_bf16 v[32:35], v[184:187], v[208:211], v[32:35]
	ds_read_b128 v[208:211], v225 offset:10240
	s_add_u32 m0, s97, 0x14000
	s_add_u32 s10, s100, 0x18000
	s_addc_u32 s11, s101, 0
	global_load_lds_dwordx4 v224, s[10:11]
	v_mfma_f32_16x16x32_bf16 v[28:31], v[168:171], v[212:215], v[28:31]
	v_mfma_f32_16x16x32_bf16 v[24:27], v[176:179], v[212:215], v[24:27]
	v_mfma_f32_16x16x32_bf16 v[20:23], v[180:183], v[212:215], v[20:23]
	v_mfma_f32_16x16x32_bf16 v[16:19], v[184:187], v[212:215], v[16:19]
	ds_read_b128 v[212:215], v225 offset:12288
	s_add_u32 m0, s97, 0x6000
	s_add_u32 s10, s98, 0x24000
	s_addc_u32 s11, s99, 0
	global_load_lds_dwordx4 v224, s[10:11]
	v_mfma_f32_16x16x32_bf16 v[12:15], v[168:171], v[220:223], v[12:15]
	v_mfma_f32_16x16x32_bf16 v[8:11], v[176:179], v[220:223], v[8:11]
	v_mfma_f32_16x16x32_bf16 v[4:7], v[180:183], v[220:223], v[4:7]
	v_mfma_f32_16x16x32_bf16 v[0:3], v[184:187], v[220:223], v[0:3]
	s_add_u32 m0, s97, 0x16000
	s_add_u32 s10, s100, 0x24000
	s_addc_u32 s11, s101, 0
	global_load_lds_dwordx4 v224, s[10:11]
	v_xor_b32_e32 v225, 0x8000, v225
	v_xor_b32_e32 v227, 0x8000, v227
	v_xor_b32_e32 v226, 0x8000, v226
	v_xor_b32_e32 v228, 0x8000, v228
	s_xor_b32 s97, s97, 0x8000
	s_add_u32 s98, s98, 0x80
	s_addc_u32 s99, s99, 0
	s_add_u32 s100, s100, 0x80
	s_addc_u32 s101, s101, 0
	s_sub_u32 s28, s28, 1
	s_cmp_lg_u32 s28, 0
	s_cbranch_scc1 .Lgm8_loop
	s_waitcnt lgkmcnt(4)
	v_mfma_f32_16x16x32_bf16 v[124:127], v[152:155], v[188:191], v[124:127]
	v_mfma_f32_16x16x32_bf16 v[120:123], v[156:159], v[188:191], v[120:123]
	v_mfma_f32_16x16x32_bf16 v[116:119], v[160:163], v[188:191], v[116:119]
	v_mfma_f32_16x16x32_bf16 v[112:115], v[164:167], v[188:191], v[112:115]
	ds_read_b128 v[188:191], v226 offset:0
	ds_read_b128 v[168:171], v228 offset:0
	v_mfma_f32_16x16x32_bf16 v[108:111], v[152:155], v[192:195], v[108:111]
	v_mfma_f32_16x16x32_bf16 v[104:107], v[156:159], v[192:195], v[104:107]
	v_mfma_f32_16x16x32_bf16 v[100:103], v[160:163], v[192:195], v[100:103]
	v_mfma_f32_16x16x32_bf16 v[96:99], v[164:167], v[192:195], v[96:99]
	ds_read_b128 v[192:195], v226 offset:2048
	ds_read_b128 v[176:179], v228 offset:2048
	v_mfma_f32_16x16x32_bf16 v[92:95], v[152:155], v[196:199], v[92:95]
	v_mfma_f32_16x16x32_bf16 v[88:91], v[156:159], v[196:199], v[88:91]
	v_mfma_f32_16x16x32_bf16 v[84:87], v[160:163], v[196:199], v[84:87]
	v_mfma_f32_16x16x32_bf16 v[80:83], v[164:167], v[196:199], v[80:83]
	ds_read_b128 v[196:199], v226 offset:4096
	ds_read_b128 v[180:183], v228 offset:4096
	v_mfma_f32_16x16x32_bf16 v[76:79], v[152:155], v[200:203], v[76:79]
	v_mfma_f32_16x16x32_bf16 v[72:75], v[156:159], v[200:203], v[72:75]
	v_mfma_f32_16x16x32_bf16 v[68:71], v[160:163], v[200:203], v[68:71]
	v_mfma_f32_16x16x32_bf16 v[64:67], v[164:167], v[200:203], v[64:67]
	ds_read_b128 v[200:203], v226 offset:6144
	ds_read_b128 v[184:187], v228 offset:6144
	s_waitcnt lgkmcnt(11)
	v_mfma_f32_16x16x32_bf16 v[60:63], v[152:155], v[204:207], v[60:63]
	v_mfma_f32_16x16x32_bf16 v[56:59], v[156:159], v[204:207], v[56:59]
	v_mfma_f32_16x16x32_bf16 v[52:55], v[160:163], v[204:207], v[52:55]
	v_mfma_f32_16x16x32_bf16 v[48:51], v[164:167], v[204:207], v[48:51]
	ds_read_b128 v[204:207], v226 offset:8192
	ds_read_b128 v[220:223], v226 offset:14336
	s_waitcnt lgkmcnt(11)
	v_mfma_f32_16x16x32_bf16 v[44:47], v[152:155], v[208:211], v[44:47]
	v_mfma_f32_16x16x32_bf16 v[40:43], v[156:159], v[208:211], v[40:43]
	v_mfma_f32_16x16x32_bf16 v[36:39], v[160:163], v[208:211], v[36:39]
	v_mfma_f32_16x16x32_bf16 v[32:35], v[164:167], v[208:211], v[32:35]
	ds_read_b128 v[208:211], v226 offset:10240
	s_waitcnt lgkmcnt(11)
	v_mfma_f32_16x16x32_bf16 v[28:31], v[152:155], v[212:215], v[28:31]
	v_mfma_f32_16x16x32_bf16 v[24:27], v[156:159], v[212:215], v[24:27]
	v_mfma_f32_16x16x32_bf16 v[20:23], v[160:163], v[212:215], v[20:23]
	v_mfma_f32_16x16x32_bf16 v[16:19], v[164:167], v[212:215], v[16:19]
	ds_read_b128 v[212:215], v226 offset:12288
	v_mfma_f32_16x16x32_bf16 v[12:15], v[152:155], v[216:219], v[12:15]
	v_mfma_f32_16x16x32_bf16 v[8:11], v[156:159], v[216:219], v[8:11]
	v_mfma_f32_16x16x32_bf16 v[4:7], v[160:163], v[216:219], v[4:7]
	v_mfma_f32_16x16x32_bf16 v[0:3], v[164:167], v[216:219], v[0:3]
	s_waitcnt vmcnt(0) lgkmcnt(0)
	s_barrier
; #define G_LOAD(KT) do { _Pragma("unroll") for (int i = 0; i < 4; ++i) { ra[i] = *(const u32x4*)(Ag + (size_t)i * 64 * lda + (KT) * 64); rb[i] = *(const u32x4*)(Bg + (size_t)i * 64 * K + (KT) * 64); } } while (0)
; #define G_STORE(BUF) do { u16* ad = As + (BUF) * 256 * 64 + sto; u16* bd = Bs + (BUF) * 256 * 64 + sto; _Pragma("unroll") for (int i = 0; i < 4; ++i) { *(u32x4*)(ad + i * 64 * 64) = ra[i]; *(u32x4*)(bd + i * 64 * 64) = rb[i]; } } while (0)
; template <int EPI>
; DI void gemm_phase(const u16* __restrict__ A, int lda, const u16* __restrict__ Bt, int K, int N, u16* outb, int ldo,
;                    const float* r0, const float* r1, float* outf, char* lds, int bid, int nb) {
;     ...
;     for (int kt = 0; kt < nk; ++kt) {
;       const int cur = kt & 1;
;       if (kt + 1 < nk) G_LOAD(kt + 1);
;       G_MMA(cur, fo0);
;       G_MMA(cur, fo1);
;       if (kt + 1 < nk) G_STORE(cur ^ 1);
;       __syncthreads();
;     }
	v_mfma_f32_16x16x32_bf16 v[124:127], v[168:171], v[188:191], v[124:127]
	v_mfma_f32_16x16x32_bf16 v[120:123], v[176:179], v[188:191], v[120:123]
	v_mfma_f32_16x16x32_bf16 v[116:119], v[180:183], v[188:191], v[116:119]
	v_mfma_f32_16x16x32_bf16 v[112:115], v[184:187], v[188:191], v[112:115]
	ds_read_b128 v[188:191], v225 offset:0
	ds_read_b128 v[152:155], v227 offset:0
	v_mfma_f32_16x16x32_bf16 v[108:111], v[168:171], v[192:195], v[108:111]
	v_mfma_f32_16x16x32_bf16 v[104:107], v[176:179], v[192:195], v[104:107]
	v_mfma_f32_16x16x32_bf16 v[100:103], v[180:183], v[192:195], v[100:103]
	v_mfma_f32_16x16x32_bf16 v[96:99], v[184:187], v[192:195], v[96:99]
	ds_read_b128 v[192:195], v225 offset:2048
	ds_read_b128 v[156:159], v227 offset:2048
	v_mfma_f32_16x16x32_bf16 v[92:95], v[168:171], v[196:199], v[92:95]
	v_mfma_f32_16x16x32_bf16 v[88:91], v[176:179], v[196:199], v[88:91]
	v_mfma_f32_16x16x32_bf16 v[84:87], v[180:183], v[196:199], v[84:87]
	v_mfma_f32_16x16x32_bf16 v[80:83], v[184:187], v[196:199], v[80:83]
	ds_read_b128 v[196:199], v225 offset:4096
	ds_read_b128 v[160:163], v227 offset:4096
	v_mfma_f32_16x16x32_bf16 v[76:79], v[168:171], v[200:203], v[76:79]
	v_mfma_f32_16x16x32_bf16 v[72:75], v[176:179], v[200:203], v[72:75]
	v_mfma_f32_16x16x32_bf16 v[68:71], v[180:183], v[200:203], v[68:71]
	v_mfma_f32_16x16x32_bf16 v[64:67], v[184:187], v[200:203], v[64:67]
	ds_read_b128 v[200:203], v225 offset:6144
	ds_read_b128 v[164:167], v227 offset:6144
	v_mfma_f32_16x16x32_bf16 v[60:63], v[168:171], v[204:207], v[60:63]
	v_mfma_f32_16x16x32_bf16 v[56:59], v[176:179], v[204:207], v[56:59]
	v_mfma_f32_16x16x32_bf16 v[52:55], v[180:183], v[204:207], v[52:55]
	v_mfma_f32_16x16x32_bf16 v[48:51], v[184:187], v[204:207], v[48:51]
	ds_read_b128 v[204:207], v225 offset:8192
	ds_read_b128 v[216:219], v225 offset:14336
	v_mfma_f32_16x16x32_bf16 v[44:47], v[168:171], v[208:211], v[44:47]
	v_mfma_f32_16x16x32_bf16 v[40:43], v[176:179], v[208:211], v[40:43]
	v_mfma_f32_16x16x32_bf16 v[36:39], v[180:183], v[208:211], v[36:39]
	v_mfma_f32_16x16x32_bf16 v[32:35], v[184:187], v[208:211], v[32:35]
	ds_read_b128 v[208:211], v225 offset:10240
	v_mfma_f32_16x16x32_bf16 v[28:31], v[168:171], v[212:215], v[28:31]
	v_mfma_f32_16x16x32_bf16 v[24:27], v[176:179], v[212:215], v[24:27]
	v_mfma_f32_16x16x32_bf16 v[20:23], v[180:183], v[212:215], v[20:23]
	v_mfma_f32_16x16x32_bf16 v[16:19], v[184:187], v[212:215], v[16:19]
	ds_read_b128 v[212:215], v225 offset:12288
	v_mfma_f32_16x16x32_bf16 v[12:15], v[168:171], v[220:223], v[12:15]
	v_mfma_f32_16x16x32_bf16 v[8:11], v[176:179], v[220:223], v[8:11]
	v_mfma_f32_16x16x32_bf16 v[4:7], v[180:183], v[220:223], v[4:7]
	v_mfma_f32_16x16x32_bf16 v[0:3], v[184:187], v[220:223], v[0:3]
	v_xor_b32_e32 v226, 0x8000, v226
	v_xor_b32_e32 v228, 0x8000, v228
	s_waitcnt lgkmcnt(4)
	v_mfma_f32_16x16x32_bf16 v[124:127], v[152:155], v[188:191], v[124:127]
	v_mfma_f32_16x16x32_bf16 v[120:123], v[156:159], v[188:191], v[120:123]
	v_mfma_f32_16x16x32_bf16 v[116:119], v[160:163], v[188:191], v[116:119]
	v_mfma_f32_16x16x32_bf16 v[112:115], v[164:167], v[188:191], v[112:115]
	ds_read_b128 v[188:191], v226 offset:0
	ds_read_b128 v[168:171], v228 offset:0
	v_mfma_f32_16x16x32_bf16 v[108:111], v[152:155], v[192:195], v[108:111]
	v_mfma_f32_16x16x32_bf16 v[104:107], v[156:159], v[192:195], v[104:107]
	v_mfma_f32_16x16x32_bf16 v[100:103], v[160:163], v[192:195], v[100:103]
	v_mfma_f32_16x16x32_bf16 v[96:99], v[164:167], v[192:195], v[96:99]
	ds_read_b128 v[192:195], v226 offset:2048
	ds_read_b128 v[176:179], v228 offset:2048
	v_mfma_f32_16x16x32_bf16 v[92:95], v[152:155], v[196:199], v[92:95]
	v_mfma_f32_16x16x32_bf16 v[88:91], v[156:159], v[196:199], v[88:91]
	v_mfma_f32_16x16x32_bf16 v[84:87], v[160:163], v[196:199], v[84:87]
	v_mfma_f32_16x16x32_bf16 v[80:83], v[164:167], v[196:199], v[80:83]
	ds_read_b128 v[196:199], v226 offset:4096
	ds_read_b128 v[180:183], v228 offset:4096
	v_mfma_f32_16x16x32_bf16 v[76:79], v[152:155], v[200:203], v[76:79]
	v_mfma_f32_16x16x32_bf16 v[72:75], v[156:159], v[200:203], v[72:75]
	v_mfma_f32_16x16x32_bf16 v[68:71], v[160:163], v[200:203], v[68:71]
	v_mfma_f32_16x16x32_bf16 v[64:67], v[164:167], v[200:203], v[64:67]
	ds_read_b128 v[200:203], v226 offset:6144
	ds_read_b128 v[184:187], v228 offset:6144
	s_waitcnt lgkmcnt(11)
	v_mfma_f32_16x16x32_bf16 v[60:63], v[152:155], v[204:207], v[60:63]
	v_mfma_f32_16x16x32_bf16 v[56:59], v[156:159], v[204:207], v[56:59]
	v_mfma_f32_16x16x32_bf16 v[52:55], v[160:163], v[204:207], v[52:55]
	v_mfma_f32_16x16x32_bf16 v[48:51], v[164:167], v[204:207], v[48:51]
	ds_read_b128 v[204:207], v226 offset:8192
	ds_read_b128 v[220:223], v226 offset:14336
	s_waitcnt lgkmcnt(11)
	v_mfma_f32_16x16x32_bf16 v[44:47], v[152:155], v[208:211], v[44:47]
	v_mfma_f32_16x16x32_bf16 v[40:43], v[156:159], v[208:211], v[40:43]
	v_mfma_f32_16x16x32_bf16 v[36:39], v[160:163], v[208:211], v[36:39]
	v_mfma_f32_16x16x32_bf16 v[32:35], v[164:167], v[208:211], v[32:35]
	ds_read_b128 v[208:211], v226 offset:10240
	s_waitcnt lgkmcnt(11)
	v_mfma_f32_16x16x32_bf16 v[28:31], v[152:155], v[212:215], v[28:31]
	v_mfma_f32_16x16x32_bf16 v[24:27], v[156:159], v[212:215], v[24:27]
	v_mfma_f32_16x16x32_bf16 v[20:23], v[160:163], v[212:215], v[20:23]
	v_mfma_f32_16x16x32_bf16 v[16:19], v[164:167], v[212:215], v[16:19]
	ds_read_b128 v[212:215], v226 offset:12288
	v_mfma_f32_16x16x32_bf16 v[12:15], v[152:155], v[216:219], v[12:15]
	v_mfma_f32_16x16x32_bf16 v[8:11], v[156:159], v[216:219], v[8:11]
	v_mfma_f32_16x16x32_bf16 v[4:7], v[160:163], v[216:219], v[4:7]
	v_mfma_f32_16x16x32_bf16 v[0:3], v[164:167], v[216:219], v[0:3]
	s_waitcnt vmcnt(0) lgkmcnt(0)
	s_barrier
; DI u16 f2bf(float a) { return (u16)(pk2(a, 0.f) & 0xffffu); }
; #define G_LOAD(KT) do { _Pragma("unroll") for (int i = 0; i < 4; ++i) { ra[i] = *(const u32x4*)(Ag + (size_t)i * 64 * lda + (KT) * 64); rb[i] = *(const u32x4*)(Bg + (size_t)i * 64 * K + (KT) * 64); } } while (0)
; #define G_STORE(BUF) do { u16* ad = As + (BUF) * 256 * 64 + sto; u16* bd = Bs + (BUF) * 256 * 64 + sto; _Pragma("unroll") for (int i = 0; i < 4; ++i) { *(u32x4*)(ad + i * 64 * 64) = ra[i]; *(u32x4*)(bd + i * 64 * 64) = rb[i]; } } while (0)
; template <int EPI>
; DI void gemm_phase(const u16* __restrict__ A, int lda, const u16* __restrict__ Bt, int K, int N, u16* outb, int ldo,
;                    const float* r0, const float* r1, float* outf, char* lds, int bid, int nb) {
;     ...
;     for (int kt = 0; kt < nk; ++kt) {
;       const int cur = kt & 1;
;       if (kt + 1 < nk) G_LOAD(kt + 1);
;       G_MMA(cur, fo0);
;       G_MMA(cur, fo1);
;       if (kt + 1 < nk) G_STORE(cur ^ 1);
;       __syncthreads();
;     }
;     ...
;     const int mrow = tm * 256 + wr * 128 + quad * 4;
;     if constexpr (EPI == EPI_BF16) {
;       const int col = tn * 256 + wc * 64 + l15;
; #pragma unroll
;       for (int i = 0; i < 8; ++i)
; #pragma unroll
;         for (int r = 0; r < 4; ++r) {
;           u16* o0 = outb + (size_t)(mrow + i * 16 + r) * ldo + col;
;           o0[0] = f2bf(acc[i][0][r]); o0[16] = f2bf(acc[i][1][r]); o0[32] = f2bf(acc[i][2][r]); o0[48] = f2bf(acc[i][3][r]);
;         }
	v_mfma_f32_16x16x32_bf16 v[124:127], v[168:171], v[188:191], v[124:127]
	v_mfma_f32_16x16x32_bf16 v[120:123], v[176:179], v[188:191], v[120:123]
	v_mfma_f32_16x16x32_bf16 v[116:119], v[180:183], v[188:191], v[116:119]
	v_mfma_f32_16x16x32_bf16 v[112:115], v[184:187], v[188:191], v[112:115]
	v_mfma_f32_16x16x32_bf16 v[108:111], v[168:171], v[192:195], v[108:111]
	v_mfma_f32_16x16x32_bf16 v[104:107], v[176:179], v[192:195], v[104:107]
	v_mfma_f32_16x16x32_bf16 v[100:103], v[180:183], v[192:195], v[100:103]
	v_mfma_f32_16x16x32_bf16 v[96:99], v[184:187], v[192:195], v[96:99]
	v_mfma_f32_16x16x32_bf16 v[92:95], v[168:171], v[196:199], v[92:95]
	v_mfma_f32_16x16x32_bf16 v[88:91], v[176:179], v[196:199], v[88:91]
	v_mfma_f32_16x16x32_bf16 v[84:87], v[180:183], v[196:199], v[84:87]
	v_mfma_f32_16x16x32_bf16 v[80:83], v[184:187], v[196:199], v[80:83]
	v_mfma_f32_16x16x32_bf16 v[76:79], v[168:171], v[200:203], v[76:79]
	v_mfma_f32_16x16x32_bf16 v[72:75], v[176:179], v[200:203], v[72:75]
	v_mfma_f32_16x16x32_bf16 v[68:71], v[180:183], v[200:203], v[68:71]
	v_mfma_f32_16x16x32_bf16 v[64:67], v[184:187], v[200:203], v[64:67]
	v_mfma_f32_16x16x32_bf16 v[60:63], v[168:171], v[204:207], v[60:63]
	v_mfma_f32_16x16x32_bf16 v[56:59], v[176:179], v[204:207], v[56:59]
	v_mfma_f32_16x16x32_bf16 v[52:55], v[180:183], v[204:207], v[52:55]
	v_mfma_f32_16x16x32_bf16 v[48:51], v[184:187], v[204:207], v[48:51]
	v_mfma_f32_16x16x32_bf16 v[44:47], v[168:171], v[208:211], v[44:47]
	v_mfma_f32_16x16x32_bf16 v[40:43], v[176:179], v[208:211], v[40:43]
	v_mfma_f32_16x16x32_bf16 v[36:39], v[180:183], v[208:211], v[36:39]
	v_mfma_f32_16x16x32_bf16 v[32:35], v[184:187], v[208:211], v[32:35]
	v_mfma_f32_16x16x32_bf16 v[28:31], v[168:171], v[212:215], v[28:31]
	v_mfma_f32_16x16x32_bf16 v[24:27], v[176:179], v[212:215], v[24:27]
	v_mfma_f32_16x16x32_bf16 v[20:23], v[180:183], v[212:215], v[20:23]
	v_mfma_f32_16x16x32_bf16 v[16:19], v[184:187], v[212:215], v[16:19]
	v_mfma_f32_16x16x32_bf16 v[12:15], v[168:171], v[220:223], v[12:15]
	v_mfma_f32_16x16x32_bf16 v[8:11], v[176:179], v[220:223], v[8:11]
	v_mfma_f32_16x16x32_bf16 v[4:7], v[180:183], v[220:223], v[4:7]
	v_mfma_f32_16x16x32_bf16 v[0:3], v[184:187], v[220:223], v[0:3]
	s_nop 7
	s_nop 3
	v_and_b32_e32 v225, 15, v174
	v_lshrrev_b32_e32 v226, 8, v174
	v_lshl_or_b32 v225, v226, 7, v225
	v_bfe_u32 v226, v174, 6, 2
	v_bfe_u32 v227, v174, 4, 2
	v_lshlrev_b32_e32 v227, 2, v227
	v_add_u32_e32 v225, s29, v225
	v_lshl_add_u32 v226, v226, 6, v227
	v_add_u32_e32 v226, s96, v226
	v_lshlrev_b32_e32 v226, 1, v226
	v_mov_b32_e32 v227, 0xc00
	v_mad_u32_u24 v224, v225, v227, v226
	v_cvt_pk_bf16_f32 v188, v124, v125
	v_cvt_pk_bf16_f32 v189, v126, v127
	global_store_dwordx2 v224, v[188:189], s[0:1] offset:0
	v_cvt_pk_bf16_f32 v190, v120, v121
	v_cvt_pk_bf16_f32 v191, v122, v123
	global_store_dwordx2 v224, v[190:191], s[0:1] offset:32
	v_cvt_pk_bf16_f32 v192, v116, v117
	v_cvt_pk_bf16_f32 v193, v118, v119
	global_store_dwordx2 v224, v[192:193], s[0:1] offset:64
	v_cvt_pk_bf16_f32 v194, v112, v113
	v_cvt_pk_bf16_f32 v195, v114, v115
	global_store_dwordx2 v224, v[194:195], s[0:1] offset:96
	v_add_u32_e32 v224, 0xc000, v224
	v_cvt_pk_bf16_f32 v196, v108, v109
	v_cvt_pk_bf16_f32 v197, v110, v111
	global_store_dwordx2 v224, v[196:197], s[0:1] offset:0
	v_cvt_pk_bf16_f32 v198, v104, v105
	v_cvt_pk_bf16_f32 v199, v106, v107
	global_store_dwordx2 v224, v[198:199], s[0:1] offset:32
	v_cvt_pk_bf16_f32 v200, v100, v101
	v_cvt_pk_bf16_f32 v201, v102, v103
	global_store_dwordx2 v224, v[200:201], s[0:1] offset:64
	v_cvt_pk_bf16_f32 v202, v96, v97
	v_cvt_pk_bf16_f32 v203, v98, v99
	global_store_dwordx2 v224, v[202:203], s[0:1] offset:96
	v_add_u32_e32 v224, 0xc000, v224
	v_cvt_pk_bf16_f32 v204, v92, v93
	v_cvt_pk_bf16_f32 v205, v94, v95
	global_store_dwordx2 v224, v[204:205], s[0:1] offset:0
	v_cvt_pk_bf16_f32 v206, v88, v89
	v_cvt_pk_bf16_f32 v207, v90, v91
	global_store_dwordx2 v224, v[206:207], s[0:1] offset:32
	v_cvt_pk_bf16_f32 v208, v84, v85
	v_cvt_pk_bf16_f32 v209, v86, v87
	global_store_dwordx2 v224, v[208:209], s[0:1] offset:64
	v_cvt_pk_bf16_f32 v210, v80, v81
	v_cvt_pk_bf16_f32 v211, v82, v83
	global_store_dwordx2 v224, v[210:211], s[0:1] offset:96
	v_add_u32_e32 v224, 0xc000, v224
	v_cvt_pk_bf16_f32 v212, v76, v77
	v_cvt_pk_bf16_f32 v213, v78, v79
	global_store_dwordx2 v224, v[212:213], s[0:1] offset:0
	v_cvt_pk_bf16_f32 v214, v72, v73
	v_cvt_pk_bf16_f32 v215, v74, v75
	global_store_dwordx2 v224, v[214:215], s[0:1] offset:32
	v_cvt_pk_bf16_f32 v216, v68, v69
	v_cvt_pk_bf16_f32 v217, v70, v71
	global_store_dwordx2 v224, v[216:217], s[0:1] offset:64
	v_cvt_pk_bf16_f32 v218, v64, v65
	v_cvt_pk_bf16_f32 v219, v66, v67
	global_store_dwordx2 v224, v[218:219], s[0:1] offset:96
	v_add_u32_e32 v224, 0xc000, v224
	v_cvt_pk_bf16_f32 v188, v60, v61
	v_cvt_pk_bf16_f32 v189, v62, v63
	global_store_dwordx2 v224, v[188:189], s[0:1] offset:0
	v_cvt_pk_bf16_f32 v190, v56, v57
	v_cvt_pk_bf16_f32 v191, v58, v59
	global_store_dwordx2 v224, v[190:191], s[0:1] offset:32
	v_cvt_pk_bf16_f32 v192, v52, v53
	v_cvt_pk_bf16_f32 v193, v54, v55
	global_store_dwordx2 v224, v[192:193], s[0:1] offset:64
	v_cvt_pk_bf16_f32 v194, v48, v49
	v_cvt_pk_bf16_f32 v195, v50, v51
	global_store_dwordx2 v224, v[194:195], s[0:1] offset:96
	v_add_u32_e32 v224, 0xc000, v224
	v_cvt_pk_bf16_f32 v196, v44, v45
	v_cvt_pk_bf16_f32 v197, v46, v47
	global_store_dwordx2 v224, v[196:197], s[0:1] offset:0
	v_cvt_pk_bf16_f32 v198, v40, v41
	v_cvt_pk_bf16_f32 v199, v42, v43
	global_store_dwordx2 v224, v[198:199], s[0:1] offset:32
	v_cvt_pk_bf16_f32 v200, v36, v37
	v_cvt_pk_bf16_f32 v201, v38, v39
	global_store_dwordx2 v224, v[200:201], s[0:1] offset:64
	v_cvt_pk_bf16_f32 v202, v32, v33
	v_cvt_pk_bf16_f32 v203, v34, v35
	global_store_dwordx2 v224, v[202:203], s[0:1] offset:96
	v_add_u32_e32 v224, 0xc000, v224
	v_cvt_pk_bf16_f32 v204, v28, v29
	v_cvt_pk_bf16_f32 v205, v30, v31
	global_store_dwordx2 v224, v[204:205], s[0:1] offset:0
	v_cvt_pk_bf16_f32 v206, v24, v25
	v_cvt_pk_bf16_f32 v207, v26, v27
	global_store_dwordx2 v224, v[206:207], s[0:1] offset:32
	v_cvt_pk_bf16_f32 v208, v20, v21
	v_cvt_pk_bf16_f32 v209, v22, v23
	global_store_dwordx2 v224, v[208:209], s[0:1] offset:64
	v_cvt_pk_bf16_f32 v210, v16, v17
	v_cvt_pk_bf16_f32 v211, v18, v19
	global_store_dwordx2 v224, v[210:211], s[0:1] offset:96
	v_add_u32_e32 v224, 0xc000, v224
	v_cvt_pk_bf16_f32 v212, v12, v13
	v_cvt_pk_bf16_f32 v213, v14, v15
	global_store_dwordx2 v224, v[212:213], s[0:1] offset:0
	v_cvt_pk_bf16_f32 v214, v8, v9
	v_cvt_pk_bf16_f32 v215, v10, v11
	global_store_dwordx2 v224, v[214:215], s[0:1] offset:32
	v_cvt_pk_bf16_f32 v216, v4, v5
	v_cvt_pk_bf16_f32 v217, v6, v7
	global_store_dwordx2 v224, v[216:217], s[0:1] offset:64
	v_cvt_pk_bf16_f32 v218, v0, v1
	v_cvt_pk_bf16_f32 v219, v2, v3
	global_store_dwordx2 v224, v[218:219], s[0:1] offset:96
	s_add_i32 s19, s19, 1
	s_add_i32 s18, s18, 16
	s_add_i32 s36, s36, 8
	s_add_i32 s16, s16, -1
	s_add_i32 s35, s35, s88
	s_cmp_lg_u32 s16, 0
	s_cbranch_scc0 .LBB0_1004

; #define G_LOAD(KT) do { _Pragma("unroll") for (int i = 0; i < 4; ++i) { ra[i] = *(const u32x4*)(Ag + (size_t)i * 64 * lda + (KT) * 64); rb[i] = *(const u32x4*)(Bg + (size_t)i * 64 * K + (KT) * 64); } } while (0)
; #define G_STORE(BUF) do { u16* ad = As + (BUF) * 256 * 64 + sto; u16* bd = Bs + (BUF) * 256 * 64 + sto; _Pragma("unroll") for (int i = 0; i < 4; ++i) { *(u32x4*)(ad + i * 64 * 64) = ra[i]; *(u32x4*)(bd + i * 64 * 64) = rb[i]; } } while (0)
; template <int EPI>
; DI void gemm_phase(const u16* __restrict__ A, int lda, const u16* __restrict__ Bt, int K, int N, u16* outb, int ldo,
;                    const float* r0, const float* r1, float* outf, char* lds, int bid, int nb) {
;     ...
;     if (swz) { const int st = xcd + 8 * it, sm = st / nSN, sn = st - sm * nSN; tm = sm * GM + jb / GN; tn = sn * GN + (jb % GN); }
;     else { const int t = bid + it * nb; tm = t / nN; tn = t - tm * nN; }
;     const u16* Ag = A + (size_t)(tm * 256 + lrow) * lda + lch * 8;
;     const u16* Bg = Bt + (size_t)(tn * 256 + lrow) * K + lch * 8;
;     f32x4 acc[8][4];
; #pragma unroll
;     for (int i = 0; i < 8; ++i)
; #pragma unroll
;       for (int j = 0; j < 4; ++j) acc[i][j] = (f32x4){0.f, 0.f, 0.f, 0.f};
;     u32x4 ra[4], rb[4];
;     ...
;     G_LOAD(0);
;     G_STORE(0);
;     __syncthreads();
;     for (int kt = 0; kt < nk; ++kt) {
;       const int cur = kt & 1;
;       if (kt + 1 < nk) G_LOAD(kt + 1);
;       G_MMA(cur, fo0);
;       G_MMA(cur, fo1);
.LBB0_1008:
	s_lshl_b32 s19, s19, 8
	s_lshl_b32 s96, s20, 8
	v_readfirstlane_b32 vcc_hi, v174
	s_lshr_b32 vcc_hi, vcc_hi, 6
	s_lshl_b32 vcc_hi, vcc_hi, 3
	s_add_u32 vcc_lo, vcc_hi, s19
	s_mul_i32 vcc_lo, vcc_lo, 0x200
	s_add_u32 s98, s24, vcc_lo
	s_addc_u32 s99, s25, 0
	s_add_u32 s98, s98, 0x5a00000
	s_addc_u32 s99, s99, 0
	s_add_u32 vcc_lo, vcc_hi, s96
	s_mul_i32 vcc_lo, vcc_lo, 0x200
	s_add_u32 s100, s24, vcc_lo
	s_addc_u32 s101, s25, 0
	s_add_u32 s100, s100, 0x1a20000
	s_addc_u32 s101, s101, 0
	v_and_b32_e32 v229, 63, v174
	v_lshrrev_b32_e32 v230, 3, v229
	v_mov_b32_e32 v233, 0x200
	v_mul_u32_u24_e32 v224, v230, v233
	v_bfe_u32 v231, v174, 4, 2
	v_bfe_u32 v232, v174, 6, 1
	v_lshl_or_b32 v232, v232, 2, v231
	v_and_b32_e32 v233, 7, v174
	v_xor_b32_e32 v232, v232, v233
	v_lshl_add_u32 v224, v232, 4, v224
	v_and_b32_e32 v229, 15, v174
	v_bfe_u32 v230, v174, 1, 3
	v_xor_b32_e32 v230, v230, v231
	v_lshlrev_b32_e32 v230, 4, v230
	v_lshl_or_b32 v230, v229, 7, v230
	v_lshrrev_b32_e32 v229, 8, v174
	v_lshl_or_b32 v225, v229, 14, v230
	v_bfe_u32 v229, v174, 6, 2
	v_lshl_or_b32 v227, v229, 13, v230
	v_or_b32_e32 v227, 0x10000, v227
	v_xor_b32_e32 v226, 64, v225
	v_xor_b32_e32 v228, 64, v227
	v_readfirstlane_b32 s97, v174
	s_lshl_b32 s97, s97, 4
	s_mov_b32 s28, 2
	s_add_u32 m0, s97, 0x0
	s_add_u32 s20, s98, 0x0
	s_addc_u32 s21, s99, 0
	global_load_lds_dwordx4 v224, s[20:21]
	s_add_u32 m0, s97, 0x10000
	s_add_u32 s20, s100, 0x0
	s_addc_u32 s21, s101, 0
	global_load_lds_dwordx4 v224, s[20:21]
	s_add_u32 m0, s97, 0x2000
	s_add_u32 s20, s98, 0x8000
	s_addc_u32 s21, s99, 0
	global_load_lds_dwordx4 v224, s[20:21]
	s_add_u32 m0, s97, 0x12000
	s_add_u32 s20, s100, 0x8000
	s_addc_u32 s21, s101, 0
	global_load_lds_dwordx4 v224, s[20:21]
	s_add_u32 m0, s97, 0x4000
	s_add_u32 s20, s98, 0x10000
	s_addc_u32 s21, s99, 0
	global_load_lds_dwordx4 v224, s[20:21]
	s_add_u32 m0, s97, 0x14000
	s_add_u32 s20, s100, 0x10000
	s_addc_u32 s21, s101, 0
	global_load_lds_dwordx4 v224, s[20:21]
	s_add_u32 m0, s97, 0x6000
	s_add_u32 s20, s98, 0x18000
	s_addc_u32 s21, s99, 0
	global_load_lds_dwordx4 v224, s[20:21]
	s_add_u32 m0, s97, 0x16000
	s_add_u32 s20, s100, 0x18000
	s_addc_u32 s21, s101, 0
	global_load_lds_dwordx4 v224, s[20:21]
	s_add_u32 m0, s97, 0x8000
	s_add_u32 s20, s98, 0x80
	s_addc_u32 s21, s99, 0
	global_load_lds_dwordx4 v224, s[20:21]
	s_add_u32 m0, s97, 0x18000
	s_add_u32 s20, s100, 0x80
	s_addc_u32 s21, s101, 0
	global_load_lds_dwordx4 v224, s[20:21]
	s_add_u32 m0, s97, 0xa000
	s_add_u32 s20, s98, 0x8080
	s_addc_u32 s21, s99, 0
	global_load_lds_dwordx4 v224, s[20:21]
	s_add_u32 m0, s97, 0x1a000
	s_add_u32 s20, s100, 0x8080
	s_addc_u32 s21, s101, 0
	global_load_lds_dwordx4 v224, s[20:21]
	s_add_u32 m0, s97, 0xc000
	s_add_u32 s20, s98, 0x10080
	s_addc_u32 s21, s99, 0
	global_load_lds_dwordx4 v224, s[20:21]
	s_add_u32 m0, s97, 0x1c000
	s_add_u32 s20, s100, 0x10080
	s_addc_u32 s21, s101, 0
	global_load_lds_dwordx4 v224, s[20:21]
	s_add_u32 m0, s97, 0xe000
	s_add_u32 s20, s98, 0x18080
	s_addc_u32 s21, s99, 0
	global_load_lds_dwordx4 v224, s[20:21]
	s_add_u32 m0, s97, 0x1e000
	s_add_u32 s20, s100, 0x18080
	s_addc_u32 s21, s101, 0
	global_load_lds_dwordx4 v224, s[20:21]
	s_add_u32 s98, s98, 0x100
	s_addc_u32 s99, s99, 0
	s_add_u32 s100, s100, 0x100
	s_addc_u32 s101, s101, 0
	s_waitcnt vmcnt(8)
	s_barrier
	ds_read_b128 v[152:155], v227 offset:0
	ds_read_b128 v[156:159], v227 offset:2048
	ds_read_b128 v[160:163], v227 offset:4096
	ds_read_b128 v[164:167], v227 offset:6144
	ds_read_b128 v[188:191], v225 offset:0
	ds_read_b128 v[192:195], v225 offset:2048
	ds_read_b128 v[196:199], v225 offset:4096
	ds_read_b128 v[200:203], v225 offset:6144
	ds_read_b128 v[204:207], v225 offset:8192
	ds_read_b128 v[208:211], v225 offset:10240
	ds_read_b128 v[212:215], v225 offset:12288
	ds_read_b128 v[216:219], v225 offset:14336
	v_xor_b32_e32 v225, 0x8000, v225
	v_xor_b32_e32 v227, 0x8000, v227
	s_waitcnt lgkmcnt(0)
	s_waitcnt lgkmcnt(4)
	v_mfma_f32_16x16x32_bf16 v[124:127], v[152:155], v[188:191], 0
	v_mfma_f32_16x16x32_bf16 v[120:123], v[156:159], v[188:191], 0
	v_mfma_f32_16x16x32_bf16 v[116:119], v[160:163], v[188:191], 0
	v_mfma_f32_16x16x32_bf16 v[112:115], v[164:167], v[188:191], 0
	ds_read_b128 v[188:191], v226 offset:0
	ds_read_b128 v[168:171], v228 offset:0
	v_mfma_f32_16x16x32_bf16 v[108:111], v[152:155], v[192:195], 0
	v_mfma_f32_16x16x32_bf16 v[104:107], v[156:159], v[192:195], 0
	v_mfma_f32_16x16x32_bf16 v[100:103], v[160:163], v[192:195], 0
	v_mfma_f32_16x16x32_bf16 v[96:99], v[164:167], v[192:195], 0
	ds_read_b128 v[192:195], v226 offset:2048
	ds_read_b128 v[176:179], v228 offset:2048
	v_mfma_f32_16x16x32_bf16 v[92:95], v[152:155], v[196:199], 0
	v_mfma_f32_16x16x32_bf16 v[88:91], v[156:159], v[196:199], 0
	v_mfma_f32_16x16x32_bf16 v[84:87], v[160:163], v[196:199], 0
	v_mfma_f32_16x16x32_bf16 v[80:83], v[164:167], v[196:199], 0
	ds_read_b128 v[196:199], v226 offset:4096
	ds_read_b128 v[180:183], v228 offset:4096
	v_mfma_f32_16x16x32_bf16 v[76:79], v[152:155], v[200:203], 0
	v_mfma_f32_16x16x32_bf16 v[72:75], v[156:159], v[200:203], 0
	v_mfma_f32_16x16x32_bf16 v[68:71], v[160:163], v[200:203], 0
	v_mfma_f32_16x16x32_bf16 v[64:67], v[164:167], v[200:203], 0
	ds_read_b128 v[200:203], v226 offset:6144
	ds_read_b128 v[184:187], v228 offset:6144
	s_waitcnt lgkmcnt(11)
	v_mfma_f32_16x16x32_bf16 v[60:63], v[152:155], v[204:207], 0
	v_mfma_f32_16x16x32_bf16 v[56:59], v[156:159], v[204:207], 0
	v_mfma_f32_16x16x32_bf16 v[52:55], v[160:163], v[204:207], 0
	v_mfma_f32_16x16x32_bf16 v[48:51], v[164:167], v[204:207], 0
	ds_read_b128 v[204:207], v226 offset:8192
	ds_read_b128 v[220:223], v226 offset:14336
	s_waitcnt lgkmcnt(11)
	v_mfma_f32_16x16x32_bf16 v[44:47], v[152:155], v[208:211], 0
	v_mfma_f32_16x16x32_bf16 v[40:43], v[156:159], v[208:211], 0
	v_mfma_f32_16x16x32_bf16 v[36:39], v[160:163], v[208:211], 0
	v_mfma_f32_16x16x32_bf16 v[32:35], v[164:167], v[208:211], 0
	ds_read_b128 v[208:211], v226 offset:10240
	s_waitcnt lgkmcnt(11)
	v_mfma_f32_16x16x32_bf16 v[28:31], v[152:155], v[212:215], 0
	v_mfma_f32_16x16x32_bf16 v[24:27], v[156:159], v[212:215], 0
	v_mfma_f32_16x16x32_bf16 v[20:23], v[160:163], v[212:215], 0
	v_mfma_f32_16x16x32_bf16 v[16:19], v[164:167], v[212:215], 0
	ds_read_b128 v[212:215], v226 offset:12288
	v_mfma_f32_16x16x32_bf16 v[12:15], v[152:155], v[216:219], 0
	v_mfma_f32_16x16x32_bf16 v[8:11], v[156:159], v[216:219], 0
	v_mfma_f32_16x16x32_bf16 v[4:7], v[160:163], v[216:219], 0
	v_mfma_f32_16x16x32_bf16 v[0:3], v[164:167], v[216:219], 0
	s_branch .Lgm9_mid0

; #define G_LOAD(KT) do { _Pragma("unroll") for (int i = 0; i < 4; ++i) { ra[i] = *(const u32x4*)(Ag + (size_t)i * 64 * lda + (KT) * 64); rb[i] = *(const u32x4*)(Bg + (size_t)i * 64 * K + (KT) * 64); } } while (0)
; #define G_STORE(BUF) do { u16* ad = As + (BUF) * 256 * 64 + sto; u16* bd = Bs + (BUF) * 256 * 64 + sto; _Pragma("unroll") for (int i = 0; i < 4; ++i) { *(u32x4*)(ad + i * 64 * 64) = ra[i]; *(u32x4*)(bd + i * 64 * 64) = rb[i]; } } while (0)
; template <int EPI>
; DI void gemm_phase(const u16* __restrict__ A, int lda, const u16* __restrict__ Bt, int K, int N, u16* outb, int ldo,
;                    const float* r0, const float* r1, float* outf, char* lds, int bid, int nb) {
;     ...
;     for (int kt = 0; kt < nk; ++kt) {
;       const int cur = kt & 1;
;       if (kt + 1 < nk) G_LOAD(kt + 1);
;       G_MMA(cur, fo0);
;       G_MMA(cur, fo1);
;       if (kt + 1 < nk) G_STORE(cur ^ 1);
;       __syncthreads();
;     }
.Lgm9_mid0:
	s_waitcnt vmcnt(0) lgkmcnt(0)
	s_barrier
	v_mfma_f32_16x16x32_bf16 v[124:127], v[168:171], v[188:191], v[124:127]
	v_mfma_f32_16x16x32_bf16 v[120:123], v[176:179], v[188:191], v[120:123]
	v_mfma_f32_16x16x32_bf16 v[116:119], v[180:183], v[188:191], v[116:119]
	v_mfma_f32_16x16x32_bf16 v[112:115], v[184:187], v[188:191], v[112:115]
	ds_read_b128 v[188:191], v225 offset:0
	ds_read_b128 v[152:155], v227 offset:0
	s_add_u32 m0, s97, 0x0
	s_add_u32 s20, s98, 0x0
	s_addc_u32 s21, s99, 0
	global_load_lds_dwordx4 v224, s[20:21]
	v_mfma_f32_16x16x32_bf16 v[108:111], v[168:171], v[192:195], v[108:111]
	v_mfma_f32_16x16x32_bf16 v[104:107], v[176:179], v[192:195], v[104:107]
	v_mfma_f32_16x16x32_bf16 v[100:103], v[180:183], v[192:195], v[100:103]
	v_mfma_f32_16x16x32_bf16 v[96:99], v[184:187], v[192:195], v[96:99]
	ds_read_b128 v[192:195], v225 offset:2048
	ds_read_b128 v[156:159], v227 offset:2048
	s_add_u32 m0, s97, 0x10000
	s_add_u32 s20, s100, 0x0
	s_addc_u32 s21, s101, 0
	global_load_lds_dwordx4 v224, s[20:21]
	v_mfma_f32_16x16x32_bf16 v[92:95], v[168:171], v[196:199], v[92:95]
	v_mfma_f32_16x16x32_bf16 v[88:91], v[176:179], v[196:199], v[88:91]
	v_mfma_f32_16x16x32_bf16 v[84:87], v[180:183], v[196:199], v[84:87]
	v_mfma_f32_16x16x32_bf16 v[80:83], v[184:187], v[196:199], v[80:83]
	ds_read_b128 v[196:199], v225 offset:4096
	ds_read_b128 v[160:163], v227 offset:4096
	s_add_u32 m0, s97, 0x2000
	s_add_u32 s20, s98, 0x8000
	s_addc_u32 s21, s99, 0
	global_load_lds_dwordx4 v224, s[20:21]
	v_mfma_f32_16x16x32_bf16 v[76:79], v[168:171], v[200:203], v[76:79]
	v_mfma_f32_16x16x32_bf16 v[72:75], v[176:179], v[200:203], v[72:75]
	v_mfma_f32_16x16x32_bf16 v[68:71], v[180:183], v[200:203], v[68:71]
	v_mfma_f32_16x16x32_bf16 v[64:67], v[184:187], v[200:203], v[64:67]
	ds_read_b128 v[200:203], v225 offset:6144
	ds_read_b128 v[164:167], v227 offset:6144
	s_add_u32 m0, s97, 0x12000
	s_add_u32 s20, s100, 0x8000
	s_addc_u32 s21, s101, 0
	global_load_lds_dwordx4 v224, s[20:21]
	v_mfma_f32_16x16x32_bf16 v[60:63], v[168:171], v[204:207], v[60:63]
	v_mfma_f32_16x16x32_bf16 v[56:59], v[176:179], v[204:207], v[56:59]
	v_mfma_f32_16x16x32_bf16 v[52:55], v[180:183], v[204:207], v[52:55]
	v_mfma_f32_16x16x32_bf16 v[48:51], v[184:187], v[204:207], v[48:51]
	ds_read_b128 v[204:207], v225 offset:8192
	ds_read_b128 v[216:219], v225 offset:14336
	s_add_u32 m0, s97, 0x4000
	s_add_u32 s20, s98, 0x10000
	s_addc_u32 s21, s99, 0
	global_load_lds_dwordx4 v224, s[20:21]
	v_mfma_f32_16x16x32_bf16 v[44:47], v[168:171], v[208:211], v[44:47]
	v_mfma_f32_16x16x32_bf16 v[40:43], v[176:179], v[208:211], v[40:43]
	v_mfma_f32_16x16x32_bf16 v[36:39], v[180:183], v[208:211], v[36:39]
	v_mfma_f32_16x16x32_bf16 v[32:35], v[184:187], v[208:211], v[32:35]
	ds_read_b128 v[208:211], v225 offset:10240
	s_add_u32 m0, s97, 0x14000
	s_add_u32 s20, s100, 0x10000
	s_addc_u32 s21, s101, 0
	global_load_lds_dwordx4 v224, s[20:21]
	v_mfma_f32_16x16x32_bf16 v[28:31], v[168:171], v[212:215], v[28:31]
	v_mfma_f32_16x16x32_bf16 v[24:27], v[176:179], v[212:215], v[24:27]
	v_mfma_f32_16x16x32_bf16 v[20:23], v[180:183], v[212:215], v[20:23]
	v_mfma_f32_16x16x32_bf16 v[16:19], v[184:187], v[212:215], v[16:19]
	ds_read_b128 v[212:215], v225 offset:12288
	s_add_u32 m0, s97, 0x6000
	s_add_u32 s20, s98, 0x18000
	s_addc_u32 s21, s99, 0
	global_load_lds_dwordx4 v224, s[20:21]
	v_mfma_f32_16x16x32_bf16 v[12:15], v[168:171], v[220:223], v[12:15]
	v_mfma_f32_16x16x32_bf16 v[8:11], v[176:179], v[220:223], v[8:11]
	v_mfma_f32_16x16x32_bf16 v[4:7], v[180:183], v[220:223], v[4:7]
	v_mfma_f32_16x16x32_bf16 v[0:3], v[184:187], v[220:223], v[0:3]
	s_add_u32 m0, s97, 0x16000
	s_add_u32 s20, s100, 0x18000
	s_addc_u32 s21, s101, 0
	global_load_lds_dwordx4 v224, s[20:21]
	v_xor_b32_e32 v225, 0x8000, v225
	v_xor_b32_e32 v227, 0x8000, v227
	v_xor_b32_e32 v226, 0x8000, v226
	v_xor_b32_e32 v228, 0x8000, v228
	s_xor_b32 s97, s97, 0x8000
	s_add_u32 s98, s98, 0x80
	s_addc_u32 s99, s99, 0
	s_add_u32 s100, s100, 0x80
	s_addc_u32 s101, s101, 0
	s_sub_u32 s28, s28, 1
	s_cmp_lg_u32 s28, 0
	s_cbranch_scc1 .Lgm9_loop
	s_waitcnt lgkmcnt(4)
	v_mfma_f32_16x16x32_bf16 v[124:127], v[152:155], v[188:191], v[124:127]
	v_mfma_f32_16x16x32_bf16 v[120:123], v[156:159], v[188:191], v[120:123]
	v_mfma_f32_16x16x32_bf16 v[116:119], v[160:163], v[188:191], v[116:119]
	v_mfma_f32_16x16x32_bf16 v[112:115], v[164:167], v[188:191], v[112:115]
	ds_read_b128 v[188:191], v226 offset:0
	ds_read_b128 v[168:171], v228 offset:0
	v_mfma_f32_16x16x32_bf16 v[108:111], v[152:155], v[192:195], v[108:111]
	v_mfma_f32_16x16x32_bf16 v[104:107], v[156:159], v[192:195], v[104:107]
	v_mfma_f32_16x16x32_bf16 v[100:103], v[160:163], v[192:195], v[100:103]
	v_mfma_f32_16x16x32_bf16 v[96:99], v[164:167], v[192:195], v[96:99]
	ds_read_b128 v[192:195], v226 offset:2048
	ds_read_b128 v[176:179], v228 offset:2048
	v_mfma_f32_16x16x32_bf16 v[92:95], v[152:155], v[196:199], v[92:95]
	v_mfma_f32_16x16x32_bf16 v[88:91], v[156:159], v[196:199], v[88:91]
	v_mfma_f32_16x16x32_bf16 v[84:87], v[160:163], v[196:199], v[84:87]
	v_mfma_f32_16x16x32_bf16 v[80:83], v[164:167], v[196:199], v[80:83]
	ds_read_b128 v[196:199], v226 offset:4096
	ds_read_b128 v[180:183], v228 offset:4096
	v_mfma_f32_16x16x32_bf16 v[76:79], v[152:155], v[200:203], v[76:79]
	v_mfma_f32_16x16x32_bf16 v[72:75], v[156:159], v[200:203], v[72:75]
	v_mfma_f32_16x16x32_bf16 v[68:71], v[160:163], v[200:203], v[68:71]
	v_mfma_f32_16x16x32_bf16 v[64:67], v[164:167], v[200:203], v[64:67]
	ds_read_b128 v[200:203], v226 offset:6144
	ds_read_b128 v[184:187], v228 offset:6144
	s_waitcnt lgkmcnt(11)
	v_mfma_f32_16x16x32_bf16 v[60:63], v[152:155], v[204:207], v[60:63]
	v_mfma_f32_16x16x32_bf16 v[56:59], v[156:159], v[204:207], v[56:59]
	v_mfma_f32_16x16x32_bf16 v[52:55], v[160:163], v[204:207], v[52:55]
	v_mfma_f32_16x16x32_bf16 v[48:51], v[164:167], v[204:207], v[48:51]
	ds_read_b128 v[204:207], v226 offset:8192
	ds_read_b128 v[220:223], v226 offset:14336
	s_waitcnt lgkmcnt(11)
	v_mfma_f32_16x16x32_bf16 v[44:47], v[152:155], v[208:211], v[44:47]
	v_mfma_f32_16x16x32_bf16 v[40:43], v[156:159], v[208:211], v[40:43]
	v_mfma_f32_16x16x32_bf16 v[36:39], v[160:163], v[208:211], v[36:39]
	v_mfma_f32_16x16x32_bf16 v[32:35], v[164:167], v[208:211], v[32:35]
	ds_read_b128 v[208:211], v226 offset:10240
	s_waitcnt lgkmcnt(11)
	v_mfma_f32_16x16x32_bf16 v[28:31], v[152:155], v[212:215], v[28:31]
	v_mfma_f32_16x16x32_bf16 v[24:27], v[156:159], v[212:215], v[24:27]
	v_mfma_f32_16x16x32_bf16 v[20:23], v[160:163], v[212:215], v[20:23]
	v_mfma_f32_16x16x32_bf16 v[16:19], v[164:167], v[212:215], v[16:19]
	ds_read_b128 v[212:215], v226 offset:12288
	v_mfma_f32_16x16x32_bf16 v[12:15], v[152:155], v[216:219], v[12:15]
	v_mfma_f32_16x16x32_bf16 v[8:11], v[156:159], v[216:219], v[8:11]
	v_mfma_f32_16x16x32_bf16 v[4:7], v[160:163], v[216:219], v[4:7]
	v_mfma_f32_16x16x32_bf16 v[0:3], v[164:167], v[216:219], v[0:3]
	s_waitcnt vmcnt(0) lgkmcnt(0)
	s_barrier
; #define G_LOAD(KT) do { _Pragma("unroll") for (int i = 0; i < 4; ++i) { ra[i] = *(const u32x4*)(Ag + (size_t)i * 64 * lda + (KT) * 64); rb[i] = *(const u32x4*)(Bg + (size_t)i * 64 * K + (KT) * 64); } } while (0)
; #define G_STORE(BUF) do { u16* ad = As + (BUF) * 256 * 64 + sto; u16* bd = Bs + (BUF) * 256 * 64 + sto; _Pragma("unroll") for (int i = 0; i < 4; ++i) { *(u32x4*)(ad + i * 64 * 64) = ra[i]; *(u32x4*)(bd + i * 64 * 64) = rb[i]; } } while (0)
; template <int EPI>
; DI void gemm_phase(const u16* __restrict__ A, int lda, const u16* __restrict__ Bt, int K, int N, u16* outb, int ldo,
;                    const float* r0, const float* r1, float* outf, char* lds, int bid, int nb) {
;     ...
;     for (int kt = 0; kt < nk; ++kt) {
;       const int cur = kt & 1;
;       if (kt + 1 < nk) G_LOAD(kt + 1);
;       G_MMA(cur, fo0);
;       G_MMA(cur, fo1);
;       if (kt + 1 < nk) G_STORE(cur ^ 1);
;       __syncthreads();
;     }
	v_mfma_f32_16x16x32_bf16 v[124:127], v[168:171], v[188:191], v[124:127]
	v_mfma_f32_16x16x32_bf16 v[120:123], v[176:179], v[188:191], v[120:123]
	v_mfma_f32_16x16x32_bf16 v[116:119], v[180:183], v[188:191], v[116:119]
	v_mfma_f32_16x16x32_bf16 v[112:115], v[184:187], v[188:191], v[112:115]
	ds_read_b128 v[188:191], v225 offset:0
	ds_read_b128 v[152:155], v227 offset:0
	v_mfma_f32_16x16x32_bf16 v[108:111], v[168:171], v[192:195], v[108:111]
	v_mfma_f32_16x16x32_bf16 v[104:107], v[176:179], v[192:195], v[104:107]
	v_mfma_f32_16x16x32_bf16 v[100:103], v[180:183], v[192:195], v[100:103]
	v_mfma_f32_16x16x32_bf16 v[96:99], v[184:187], v[192:195], v[96:99]
	ds_read_b128 v[192:195], v225 offset:2048
	ds_read_b128 v[156:159], v227 offset:2048
	v_mfma_f32_16x16x32_bf16 v[92:95], v[168:171], v[196:199], v[92:95]
	v_mfma_f32_16x16x32_bf16 v[88:91], v[176:179], v[196:199], v[88:91]
	v_mfma_f32_16x16x32_bf16 v[84:87], v[180:183], v[196:199], v[84:87]
	v_mfma_f32_16x16x32_bf16 v[80:83], v[184:187], v[196:199], v[80:83]
	ds_read_b128 v[196:199], v225 offset:4096
	ds_read_b128 v[160:163], v227 offset:4096
	v_mfma_f32_16x16x32_bf16 v[76:79], v[168:171], v[200:203], v[76:79]
	v_mfma_f32_16x16x32_bf16 v[72:75], v[176:179], v[200:203], v[72:75]
	v_mfma_f32_16x16x32_bf16 v[68:71], v[180:183], v[200:203], v[68:71]
	v_mfma_f32_16x16x32_bf16 v[64:67], v[184:187], v[200:203], v[64:67]
	ds_read_b128 v[200:203], v225 offset:6144
	ds_read_b128 v[164:167], v227 offset:6144
	v_mfma_f32_16x16x32_bf16 v[60:63], v[168:171], v[204:207], v[60:63]
	v_mfma_f32_16x16x32_bf16 v[56:59], v[176:179], v[204:207], v[56:59]
	v_mfma_f32_16x16x32_bf16 v[52:55], v[180:183], v[204:207], v[52:55]
	v_mfma_f32_16x16x32_bf16 v[48:51], v[184:187], v[204:207], v[48:51]
	ds_read_b128 v[204:207], v225 offset:8192
	ds_read_b128 v[216:219], v225 offset:14336
	v_mfma_f32_16x16x32_bf16 v[44:47], v[168:171], v[208:211], v[44:47]
	v_mfma_f32_16x16x32_bf16 v[40:43], v[176:179], v[208:211], v[40:43]
	v_mfma_f32_16x16x32_bf16 v[36:39], v[180:183], v[208:211], v[36:39]
	v_mfma_f32_16x16x32_bf16 v[32:35], v[184:187], v[208:211], v[32:35]
	ds_read_b128 v[208:211], v225 offset:10240
	v_mfma_f32_16x16x32_bf16 v[28:31], v[168:171], v[212:215], v[28:31]
	v_mfma_f32_16x16x32_bf16 v[24:27], v[176:179], v[212:215], v[24:27]
	v_mfma_f32_16x16x32_bf16 v[20:23], v[180:183], v[212:215], v[20:23]
	v_mfma_f32_16x16x32_bf16 v[16:19], v[184:187], v[212:215], v[16:19]
	ds_read_b128 v[212:215], v225 offset:12288
	v_mfma_f32_16x16x32_bf16 v[12:15], v[168:171], v[220:223], v[12:15]
	v_mfma_f32_16x16x32_bf16 v[8:11], v[176:179], v[220:223], v[8:11]
	v_mfma_f32_16x16x32_bf16 v[4:7], v[180:183], v[220:223], v[4:7]
	v_mfma_f32_16x16x32_bf16 v[0:3], v[184:187], v[220:223], v[0:3]
	v_xor_b32_e32 v226, 0x8000, v226
	v_xor_b32_e32 v228, 0x8000, v228
	s_waitcnt lgkmcnt(4)
	v_mfma_f32_16x16x32_bf16 v[124:127], v[152:155], v[188:191], v[124:127]
	v_mfma_f32_16x16x32_bf16 v[120:123], v[156:159], v[188:191], v[120:123]
	v_mfma_f32_16x16x32_bf16 v[116:119], v[160:163], v[188:191], v[116:119]
	v_mfma_f32_16x16x32_bf16 v[112:115], v[164:167], v[188:191], v[112:115]
	ds_read_b128 v[188:191], v226 offset:0
	ds_read_b128 v[168:171], v228 offset:0
	v_mfma_f32_16x16x32_bf16 v[108:111], v[152:155], v[192:195], v[108:111]
	v_mfma_f32_16x16x32_bf16 v[104:107], v[156:159], v[192:195], v[104:107]
	v_mfma_f32_16x16x32_bf16 v[100:103], v[160:163], v[192:195], v[100:103]
	v_mfma_f32_16x16x32_bf16 v[96:99], v[164:167], v[192:195], v[96:99]
	ds_read_b128 v[192:195], v226 offset:2048
	ds_read_b128 v[176:179], v228 offset:2048
	v_mfma_f32_16x16x32_bf16 v[92:95], v[152:155], v[196:199], v[92:95]
	v_mfma_f32_16x16x32_bf16 v[88:91], v[156:159], v[196:199], v[88:91]
	v_mfma_f32_16x16x32_bf16 v[84:87], v[160:163], v[196:199], v[84:87]
	v_mfma_f32_16x16x32_bf16 v[80:83], v[164:167], v[196:199], v[80:83]
	ds_read_b128 v[196:199], v226 offset:4096
	ds_read_b128 v[180:183], v228 offset:4096
	v_mfma_f32_16x16x32_bf16 v[76:79], v[152:155], v[200:203], v[76:79]
	v_mfma_f32_16x16x32_bf16 v[72:75], v[156:159], v[200:203], v[72:75]
	v_mfma_f32_16x16x32_bf16 v[68:71], v[160:163], v[200:203], v[68:71]
	v_mfma_f32_16x16x32_bf16 v[64:67], v[164:167], v[200:203], v[64:67]
	ds_read_b128 v[200:203], v226 offset:6144
	ds_read_b128 v[184:187], v228 offset:6144
	s_waitcnt lgkmcnt(11)
	v_mfma_f32_16x16x32_bf16 v[60:63], v[152:155], v[204:207], v[60:63]
	v_mfma_f32_16x16x32_bf16 v[56:59], v[156:159], v[204:207], v[56:59]
	v_mfma_f32_16x16x32_bf16 v[52:55], v[160:163], v[204:207], v[52:55]
	v_mfma_f32_16x16x32_bf16 v[48:51], v[164:167], v[204:207], v[48:51]
	ds_read_b128 v[204:207], v226 offset:8192
	ds_read_b128 v[220:223], v226 offset:14336
	s_waitcnt lgkmcnt(11)
	v_mfma_f32_16x16x32_bf16 v[44:47], v[152:155], v[208:211], v[44:47]
	v_mfma_f32_16x16x32_bf16 v[40:43], v[156:159], v[208:211], v[40:43]
	v_mfma_f32_16x16x32_bf16 v[36:39], v[160:163], v[208:211], v[36:39]
	v_mfma_f32_16x16x32_bf16 v[32:35], v[164:167], v[208:211], v[32:35]
	ds_read_b128 v[208:211], v226 offset:10240
	s_waitcnt lgkmcnt(11)
	v_mfma_f32_16x16x32_bf16 v[28:31], v[152:155], v[212:215], v[28:31]
	v_mfma_f32_16x16x32_bf16 v[24:27], v[156:159], v[212:215], v[24:27]
	v_mfma_f32_16x16x32_bf16 v[20:23], v[160:163], v[212:215], v[20:23]
	v_mfma_f32_16x16x32_bf16 v[16:19], v[164:167], v[212:215], v[16:19]
	ds_read_b128 v[212:215], v226 offset:12288
	v_mfma_f32_16x16x32_bf16 v[12:15], v[152:155], v[216:219], v[12:15]
	v_mfma_f32_16x16x32_bf16 v[8:11], v[156:159], v[216:219], v[8:11]
	v_mfma_f32_16x16x32_bf16 v[4:7], v[160:163], v[216:219], v[4:7]
	v_mfma_f32_16x16x32_bf16 v[0:3], v[164:167], v[216:219], v[0:3]
	s_waitcnt vmcnt(0) lgkmcnt(0)
	s_barrier
; DI u16 f2bf(float a) { return (u16)(pk2(a, 0.f) & 0xffffu); }
; #define G_LOAD(KT) do { _Pragma("unroll") for (int i = 0; i < 4; ++i) { ra[i] = *(const u32x4*)(Ag + (size_t)i * 64 * lda + (KT) * 64); rb[i] = *(const u32x4*)(Bg + (size_t)i * 64 * K + (KT) * 64); } } while (0)
; #define G_STORE(BUF) do { u16* ad = As + (BUF) * 256 * 64 + sto; u16* bd = Bs + (BUF) * 256 * 64 + sto; _Pragma("unroll") for (int i = 0; i < 4; ++i) { *(u32x4*)(ad + i * 64 * 64) = ra[i]; *(u32x4*)(bd + i * 64 * 64) = rb[i]; } } while (0)
; template <int EPI>
; DI void gemm_phase(const u16* __restrict__ A, int lda, const u16* __restrict__ Bt, int K, int N, u16* outb, int ldo,
;                    const float* r0, const float* r1, float* outf, char* lds, int bid, int nb) {
;     ...
;     for (int kt = 0; kt < nk; ++kt) {
;       const int cur = kt & 1;
;       if (kt + 1 < nk) G_LOAD(kt + 1);
;       G_MMA(cur, fo0);
;       G_MMA(cur, fo1);
;       if (kt + 1 < nk) G_STORE(cur ^ 1);
;       __syncthreads();
;     }
;     ...
;     const int mrow = tm * 256 + wr * 128 + quad * 4;
;     if constexpr (EPI == EPI_BF16) {
;       const int col = tn * 256 + wc * 64 + l15;
; #pragma unroll
;       for (int i = 0; i < 8; ++i)
; #pragma unroll
;         for (int r = 0; r < 4; ++r) {
;           u16* o0 = outb + (size_t)(mrow + i * 16 + r) * ldo + col;
;           o0[0] = f2bf(acc[i][0][r]); o0[16] = f2bf(acc[i][1][r]); o0[32] = f2bf(acc[i][2][r]); o0[48] = f2bf(acc[i][3][r]);
;         }
	v_mfma_f32_16x16x32_bf16 v[124:127], v[168:171], v[188:191], v[124:127]
	v_mfma_f32_16x16x32_bf16 v[120:123], v[176:179], v[188:191], v[120:123]
	v_mfma_f32_16x16x32_bf16 v[116:119], v[180:183], v[188:191], v[116:119]
	v_mfma_f32_16x16x32_bf16 v[112:115], v[184:187], v[188:191], v[112:115]
	v_mfma_f32_16x16x32_bf16 v[108:111], v[168:171], v[192:195], v[108:111]
	v_mfma_f32_16x16x32_bf16 v[104:107], v[176:179], v[192:195], v[104:107]
	v_mfma_f32_16x16x32_bf16 v[100:103], v[180:183], v[192:195], v[100:103]
	v_mfma_f32_16x16x32_bf16 v[96:99], v[184:187], v[192:195], v[96:99]
	v_mfma_f32_16x16x32_bf16 v[92:95], v[168:171], v[196:199], v[92:95]
	v_mfma_f32_16x16x32_bf16 v[88:91], v[176:179], v[196:199], v[88:91]
	v_mfma_f32_16x16x32_bf16 v[84:87], v[180:183], v[196:199], v[84:87]
	v_mfma_f32_16x16x32_bf16 v[80:83], v[184:187], v[196:199], v[80:83]
	v_mfma_f32_16x16x32_bf16 v[76:79], v[168:171], v[200:203], v[76:79]
	v_mfma_f32_16x16x32_bf16 v[72:75], v[176:179], v[200:203], v[72:75]
	v_mfma_f32_16x16x32_bf16 v[68:71], v[180:183], v[200:203], v[68:71]
	v_mfma_f32_16x16x32_bf16 v[64:67], v[184:187], v[200:203], v[64:67]
	v_mfma_f32_16x16x32_bf16 v[60:63], v[168:171], v[204:207], v[60:63]
	v_mfma_f32_16x16x32_bf16 v[56:59], v[176:179], v[204:207], v[56:59]
	v_mfma_f32_16x16x32_bf16 v[52:55], v[180:183], v[204:207], v[52:55]
	v_mfma_f32_16x16x32_bf16 v[48:51], v[184:187], v[204:207], v[48:51]
	v_mfma_f32_16x16x32_bf16 v[44:47], v[168:171], v[208:211], v[44:47]
	v_mfma_f32_16x16x32_bf16 v[40:43], v[176:179], v[208:211], v[40:43]
	v_mfma_f32_16x16x32_bf16 v[36:39], v[180:183], v[208:211], v[36:39]
	v_mfma_f32_16x16x32_bf16 v[32:35], v[184:187], v[208:211], v[32:35]
	v_mfma_f32_16x16x32_bf16 v[28:31], v[168:171], v[212:215], v[28:31]
	v_mfma_f32_16x16x32_bf16 v[24:27], v[176:179], v[212:215], v[24:27]
	v_mfma_f32_16x16x32_bf16 v[20:23], v[180:183], v[212:215], v[20:23]
	v_mfma_f32_16x16x32_bf16 v[16:19], v[184:187], v[212:215], v[16:19]
	v_mfma_f32_16x16x32_bf16 v[12:15], v[168:171], v[220:223], v[12:15]
	v_mfma_f32_16x16x32_bf16 v[8:11], v[176:179], v[220:223], v[8:11]
	v_mfma_f32_16x16x32_bf16 v[4:7], v[180:183], v[220:223], v[4:7]
	v_mfma_f32_16x16x32_bf16 v[0:3], v[184:187], v[220:223], v[0:3]
	s_nop 7
	s_nop 3
	v_and_b32_e32 v225, 15, v174
	v_lshrrev_b32_e32 v226, 8, v174
	v_lshl_or_b32 v225, v226, 7, v225
	v_bfe_u32 v226, v174, 6, 2
	v_bfe_u32 v227, v174, 4, 2
	v_lshlrev_b32_e32 v227, 2, v227
	v_add_u32_e32 v225, s19, v225
	v_lshl_add_u32 v226, v226, 6, v227
	v_add_u32_e32 v226, s96, v226
	v_lshlrev_b32_e32 v226, 1, v226
	v_mov_b32_e32 v227, 0x1080
	v_mad_u32_u24 v224, v225, v227, v226
	v_cvt_pk_bf16_f32 v188, v124, v125
	v_cvt_pk_bf16_f32 v189, v126, v127
	global_store_dwordx2 v224, v[188:189], s[8:9] offset:0
	v_cvt_pk_bf16_f32 v190, v120, v121
	v_cvt_pk_bf16_f32 v191, v122, v123
	global_store_dwordx2 v224, v[190:191], s[8:9] offset:32
	v_cvt_pk_bf16_f32 v192, v116, v117
	v_cvt_pk_bf16_f32 v193, v118, v119
	global_store_dwordx2 v224, v[192:193], s[8:9] offset:64
	v_cvt_pk_bf16_f32 v194, v112, v113
	v_cvt_pk_bf16_f32 v195, v114, v115
	global_store_dwordx2 v224, v[194:195], s[8:9] offset:96
	v_add_u32_e32 v224, 0x10800, v224
	v_cvt_pk_bf16_f32 v196, v108, v109
	v_cvt_pk_bf16_f32 v197, v110, v111
	global_store_dwordx2 v224, v[196:197], s[8:9] offset:0
	v_cvt_pk_bf16_f32 v198, v104, v105
	v_cvt_pk_bf16_f32 v199, v106, v107
	global_store_dwordx2 v224, v[198:199], s[8:9] offset:32
	v_cvt_pk_bf16_f32 v200, v100, v101
	v_cvt_pk_bf16_f32 v201, v102, v103
	global_store_dwordx2 v224, v[200:201], s[8:9] offset:64
	v_cvt_pk_bf16_f32 v202, v96, v97
	v_cvt_pk_bf16_f32 v203, v98, v99
	global_store_dwordx2 v224, v[202:203], s[8:9] offset:96
	v_add_u32_e32 v224, 0x10800, v224
	v_cvt_pk_bf16_f32 v204, v92, v93
	v_cvt_pk_bf16_f32 v205, v94, v95
	global_store_dwordx2 v224, v[204:205], s[8:9] offset:0
	v_cvt_pk_bf16_f32 v206, v88, v89
	v_cvt_pk_bf16_f32 v207, v90, v91
	global_store_dwordx2 v224, v[206:207], s[8:9] offset:32
	v_cvt_pk_bf16_f32 v208, v84, v85
	v_cvt_pk_bf16_f32 v209, v86, v87
	global_store_dwordx2 v224, v[208:209], s[8:9] offset:64
	v_cvt_pk_bf16_f32 v210, v80, v81
	v_cvt_pk_bf16_f32 v211, v82, v83
	global_store_dwordx2 v224, v[210:211], s[8:9] offset:96
	v_add_u32_e32 v224, 0x10800, v224
	v_cvt_pk_bf16_f32 v212, v76, v77
	v_cvt_pk_bf16_f32 v213, v78, v79
	global_store_dwordx2 v224, v[212:213], s[8:9] offset:0
	v_cvt_pk_bf16_f32 v214, v72, v73
	v_cvt_pk_bf16_f32 v215, v74, v75
	global_store_dwordx2 v224, v[214:215], s[8:9] offset:32
	v_cvt_pk_bf16_f32 v216, v68, v69
	v_cvt_pk_bf16_f32 v217, v70, v71
	global_store_dwordx2 v224, v[216:217], s[8:9] offset:64
	v_cvt_pk_bf16_f32 v218, v64, v65
	v_cvt_pk_bf16_f32 v219, v66, v67
	global_store_dwordx2 v224, v[218:219], s[8:9] offset:96
	v_add_u32_e32 v224, 0x10800, v224
	v_cvt_pk_bf16_f32 v188, v60, v61
	v_cvt_pk_bf16_f32 v189, v62, v63
	global_store_dwordx2 v224, v[188:189], s[8:9] offset:0
	v_cvt_pk_bf16_f32 v190, v56, v57
	v_cvt_pk_bf16_f32 v191, v58, v59
	global_store_dwordx2 v224, v[190:191], s[8:9] offset:32
	v_cvt_pk_bf16_f32 v192, v52, v53
	v_cvt_pk_bf16_f32 v193, v54, v55
	global_store_dwordx2 v224, v[192:193], s[8:9] offset:64
	v_cvt_pk_bf16_f32 v194, v48, v49
	v_cvt_pk_bf16_f32 v195, v50, v51
	global_store_dwordx2 v224, v[194:195], s[8:9] offset:96
	v_add_u32_e32 v224, 0x10800, v224
	v_cvt_pk_bf16_f32 v196, v44, v45
	v_cvt_pk_bf16_f32 v197, v46, v47
	global_store_dwordx2 v224, v[196:197], s[8:9] offset:0
	v_cvt_pk_bf16_f32 v198, v40, v41
	v_cvt_pk_bf16_f32 v199, v42, v43
	global_store_dwordx2 v224, v[198:199], s[8:9] offset:32
	v_cvt_pk_bf16_f32 v200, v36, v37
	v_cvt_pk_bf16_f32 v201, v38, v39
	global_store_dwordx2 v224, v[200:201], s[8:9] offset:64
	v_cvt_pk_bf16_f32 v202, v32, v33
	v_cvt_pk_bf16_f32 v203, v34, v35
	global_store_dwordx2 v224, v[202:203], s[8:9] offset:96
	v_add_u32_e32 v224, 0x10800, v224
	v_cvt_pk_bf16_f32 v204, v28, v29
	v_cvt_pk_bf16_f32 v205, v30, v31
	global_store_dwordx2 v224, v[204:205], s[8:9] offset:0
	v_cvt_pk_bf16_f32 v206, v24, v25
	v_cvt_pk_bf16_f32 v207, v26, v27
	global_store_dwordx2 v224, v[206:207], s[8:9] offset:32
	v_cvt_pk_bf16_f32 v208, v20, v21
	v_cvt_pk_bf16_f32 v209, v22, v23
	global_store_dwordx2 v224, v[208:209], s[8:9] offset:64
	v_cvt_pk_bf16_f32 v210, v16, v17
	v_cvt_pk_bf16_f32 v211, v18, v19
	global_store_dwordx2 v224, v[210:211], s[8:9] offset:96
	v_add_u32_e32 v224, 0x10800, v224
	v_cvt_pk_bf16_f32 v212, v12, v13
	v_cvt_pk_bf16_f32 v213, v14, v15
	global_store_dwordx2 v224, v[212:213], s[8:9] offset:0
	v_cvt_pk_bf16_f32 v214, v8, v9
	v_cvt_pk_bf16_f32 v215, v10, v11
	global_store_dwordx2 v224, v[214:215], s[8:9] offset:32
	v_cvt_pk_bf16_f32 v216, v4, v5
	v_cvt_pk_bf16_f32 v217, v6, v7
	global_store_dwordx2 v224, v[216:217], s[8:9] offset:64
	v_cvt_pk_bf16_f32 v218, v0, v1
	v_cvt_pk_bf16_f32 v219, v2, v3
	global_store_dwordx2 v224, v[218:219], s[8:9] offset:96
	s_add_i32 s14, s14, 32
	s_add_i32 s3, s3, -1
	s_add_i32 s18, s18, s88
	s_cmp_lg_u32 s3, 0
	s_cbranch_scc0 .LBB0_1011
